# chain loop ladder-first: older set written to LDS at half-step start, shared wait ladder, chunk+2 prefetch in prologue; MOD1 sum loads issued together
# speedup vs baseline: 1.0029x; 1.0011x over previous
; #define LAS __attribute__((address_space(3)))
; #define CH_ISSUE(ci, set) CH_ISSUE_X(ci, set)
; #define CH_WRITE(buf, set) CH_WRITE_X(buf, set)
; __device__ __forceinline__ void gla_chain(const Params& p, LAS unsigned char* lds) {
;     ...
;     CH_ISSUE(0, SET_A); CH_WRITE(0, SET_A); CH_ISSUE(1, SET_B);
;     f32x4 S[8];
; #pragma unroll
;     for (int dt = 0; dt < 8; ++dt) S[dt] = (f32x4){0.f, 0.f, 0.f, 0.f};
;     if (wave < 4) {
; #pragma unroll
;         for (int dt = 0; dt < 8; ++dt) *(LAS u32x2*)(st + fr * 272 + (dt * 16 + fq * 4) * 2) = (u32x2){0u, 0u};
;     }
;     __syncthreads();
;     ...
;     for (int ci = 0; ci < 68; ci += 2) {
;         CH_ISSUE(ci + 2, SET_A);
;         step(ci, lds);
;         CH_WRITE(1, SET_B);
.LBB0_456:
	v_lshlrev_b64 v[28:29], 13, v[28:29]
	v_lshl_add_u64 v[28:29], s[10:11], 0, v[28:29]
	v_mov_b32_e32 v144, v142
	v_mov_b32_e32 v145, v65
	v_lshl_add_u64 v[28:29], v[28:29], 0, v[144:145]
	s_mov_b64 s[2:3], 0x2141c000
	v_lshl_add_u64 v[146:147], v[28:29], 0, s[2:3]
	v_readlane_b32 s2, v239, 27
	s_add_u32 s2, s10, s2
	s_addc_u32 s3, s11, 0
	v_readlane_b32 s37, v239, 49
	s_add_u32 s2, s2, s37
	s_addc_u32 s3, s3, 0
	v_readlane_b32 s37, v239, 50
	s_add_u32 s2, s2, s37
	s_addc_u32 s3, s3, 0
	s_lshl_b32 s37, s35, 4
	s_and_b32 s37, s37, 48
	s_lshl_b32 s38, s37, 1
	s_add_u32 s2, s2, s38
	s_addc_u32 s3, s3, 0
	v_mov_b32_e32 v33, v65
	v_lshl_add_u64 v[28:29], s[2:3], 0, v[32:33]
	s_mov_b64 s[2:3], 0x134fc000
	v_mov_b32_e32 v31, v65
	v_lshl_add_u64 v[148:149], v[28:29], 0, s[2:3]
	v_lshl_add_u64 v[28:29], v[138:139], 1, s[26:27]
	v_lshl_add_u64 v[152:153], s[28:29], 0, v[30:31]
	v_readlane_b32 s3, v239, 55
	v_readlane_b32 s28, v239, 56
	v_readlane_b32 s29, v239, 57
	v_lshl_add_u64 v[150:151], v[28:29], 0, v[144:145]
	v_or_b32_e32 v28, s37, v154
	s_movk_i32 s2, 0x90
	v_lshlrev_b32_e32 v158, 4, v36
	v_add_u32_e32 v159, s3, v35
	v_add_u32_e32 v32, s28, v35
	v_add_u32_e32 v33, s29, v35
	v_mov_b32_e32 v35, s29
	v_mov_b32_e32 v98, v65
	v_mov_b32_e32 v99, v65
	v_mov_b32_e32 v100, v65
	v_mov_b32_e32 v101, v65
	v_mad_u32_u24 v29, v28, s2, 0
	s_cmp_lt_i32 s35, 4
	v_add_u32_e32 v30, s36, v158
	v_add_u32_e32 v31, 0x2400, v159
	v_mad_u32_u24 v28, v28, s2, v35
	v_mul_u32_u24_e32 v161, 0x90, v154
	v_or_b32_e32 v35, 16, v154
	v_lshlrev_b32_e32 v173, 4, v34
	v_add_u32_e32 v34, s3, v158
	v_mov_b64_e32 v[104:105], v[100:101]
	v_mov_b64_e32 v[94:95], v[98:99]
	v_mov_b64_e32 v[90:91], v[98:99]
	v_mov_b64_e32 v[74:75], v[98:99]
	v_mov_b64_e32 v[66:67], v[98:99]
	v_mov_b64_e32 v[60:61], v[98:99]
	v_mov_b64_e32 v[56:57], v[98:99]
	s_cselect_b64 s[26:27], -1, 0
	v_add_u32_e32 v160, 0, v158
	v_add_u32_e32 v170, s36, v157
	v_mul_u32_u24_e32 v171, 0x110, v35
	v_mul_u32_u24_e32 v172, 0x90, v35
	v_add_u32_e32 v174, s28, v158
	s_mov_b32 s35, 0
	v_add_u32_e32 v175, v29, v158
	v_add_u32_e32 v176, v30, v157
	v_add_u32_e32 v177, v31, v130
	v_add_u32_e32 v178, v32, v130
	v_add_u32_e32 v179, v33, v130
	v_add_u32_e32 v180, v28, v158
	v_add_u32_e32 v181, v34, v161
	v_mov_b64_e32 v[102:103], v[98:99]
	v_mov_b64_e32 v[96:97], v[100:101]
	v_mov_b64_e32 v[92:93], v[100:101]
	v_mov_b64_e32 v[76:77], v[100:101]
	v_mov_b64_e32 v[68:69], v[100:101]
	v_mov_b64_e32 v[62:63], v[100:101]
	v_mov_b64_e32 v[58:59], v[100:101]
	s_mov_b32 s37, -2
	s_add_i32 s36, s37, 2
	s_cmpk_gt_u32 s37, 0x41
	s_cselect_b64 s[28:29], -1, 0
	s_add_i32 s38, s37, 4
	s_min_u32 s38, s38, 0x43
	s_cmp_gt_u32 s38, 3
	s_cselect_b32 s2, 0x47, 3
	s_sub_i32 s39, s2, s38
	s_and_b64 s[2:3], s[78:79], exec
	s_cselect_b32 s2, s38, s39
	s_ashr_i32 s3, s2, 31
	s_lshl_b64 s[38:39], s[2:3], 13
	s_lshl_b64 s[40:41], s[2:3], 14
	s_add_u32 s42, s1, s40
	s_addc_u32 s43, s30, s41
	s_add_u32 s40, s31, s40
	s_addc_u32 s41, s34, s41
	s_cmp_lt_i32 s2, 4
	s_waitcnt vmcnt(11)
	v_lshl_add_u64 v[44:45], v[150:151], 0, s[38:39]
	s_cselect_b64 vcc, -1, 0
	s_lshl_b32 s38, s2, 6
	s_ashr_i32 s39, s38, 31
	v_lshl_add_u64 v[46:47], s[38:39], 1, v[132:133]
	s_mov_b32 s39, s73
	v_lshl_add_u64 v[48:49], s[38:39], 1, v[146:147]
	s_movk_i32 s38, 0xfe00
	s_mov_b32 s39, -1
	v_lshl_add_u64 v[28:29], v[134:135], 1, s[42:43]
	v_lshl_add_u64 v[30:31], v[136:137], 1, s[42:43]
	v_lshl_add_u64 v[36:37], v[138:139], 1, s[40:41]
	v_lshl_add_u64 v[38:39], v[140:141], 1, s[40:41]
	v_lshl_add_u64 v[48:49], v[48:49], 0, s[38:39]
	v_lshl_add_u64 v[28:29], v[28:29], 0, v[64:65]
	v_lshl_add_u64 v[32:33], v[30:31], 0, v[64:65]
	v_lshl_add_u64 v[36:37], v[36:37], 0, v[144:145]
	v_lshl_add_u64 v[40:41], v[38:39], 0, v[144:145]
	v_cndmask_b32_e32 v47, v49, v47, vcc
	v_cndmask_b32_e32 v46, v48, v46, vcc
	s_lshl_b64 s[2:3], s[2:3], 9
	global_load_dwordx4 v[28:31], v[28:29], off
	s_nop 0
	global_load_dwordx4 v[32:35], v[32:33], off
	s_nop 0
	global_load_dwordx4 v[36:39], v[36:37], off
	s_nop 0
	global_load_dwordx4 v[40:43], v[40:41], off
	global_load_dwordx4 v[48:51], v[46:47], off
	v_lshl_add_u64 v[46:47], v[152:153], 0, s[2:3]
	global_load_dwordx4 v[52:55], v[44:45], off
	s_nop 0
	global_load_dwordx4 v[44:47], v[46:47], off
	s_mov_b32 s37, 0
	s_waitcnt lgkmcnt(0)
	s_barrier
.LBB0_458:
	s_waitcnt vmcnt(13)
	ds_write_b128 v131, v[0:3] offset:54784
	s_waitcnt vmcnt(12)
	ds_write_b128 v131, v[4:7] offset:63488
	v_add_u32_e32 v0, v159, v130
	s_waitcnt vmcnt(11)
	ds_write_b128 v0, v[8:11]
	s_waitcnt vmcnt(10)
	ds_write_b128 v177, v[12:15]
	s_waitcnt vmcnt(8)
	ds_write_b128 v178, v[24:27]
	s_waitcnt vmcnt(7)
	ds_write_b128 v179, v[16:19]
	s_and_saveexec_b64 s[2:3], s[8:9]
	s_cbranch_execz .Lch_reb_done
	v_add_u32_e32 v0, 0, v173
	v_add_u32_e32 v0, 0x1aa00, v0
	s_waitcnt vmcnt(7)
	ds_write_b128 v0, v[20:23]
; #define LAS __attribute__((address_space(3)))
; __device__ __forceinline__ unsigned pk2(float lo, float hi) { const v2f_t f = {lo, hi}; const v2bf_t b = __builtin_convertvector(f, v2bf_t); return __builtin_bit_cast(unsigned, b); }
; __device__ __forceinline__ void gla_chain(const Params& p, LAS unsigned char* lds) {
;     ...
;         } else {
;             LAS unsigned char* sto = st + ((ci + 1) & 1) * (4 * 4352);
; #pragma unroll
;             for (int hh = 0; hh < 2; ++hh) {
;                 f32x4 ev[4]; bf16x8 ak[4][2];
; #pragma unroll
;                 for (int d4 = 0; d4 < 4; ++d4) { const int dt = hh * 4 + d4; ev[d4] = *(const LAS f32x4*)(cur + CH_E + (dt * 16 + fq * 4) * 4);
; #pragma unroll
;                     for (int ks = 0; ks < 2; ++ks) ak[d4][ks] = *(const LAS bf16x8*)(cur + CH_KH + (dt * 16 + fr) * 144 + ks * 64 + fq * 16); }
; #pragma unroll
;                 for (int d4 = 0; d4 < 4; ++d4) S[hh * 4 + d4] = S[hh * 4 + d4] * ev[d4];
; #pragma unroll
;                 for (int ks = 0; ks < 2; ++ks)
; #pragma unroll
;                     for (int d4 = 0; d4 < 4; ++d4) S[hh * 4 + d4] = __builtin_amdgcn_mfma_f32_16x16x32_bf16(ak[d4][ks], a_v[ks], S[hh * 4 + d4], 0, 0, 0);
;             }
; #pragma unroll
;             for (int dt = 0; dt < 8; ++dt) { u32x2 w2; w2.x = pk2(S[dt][0], S[dt][1]); w2.y = pk2(S[dt][2], S[dt][3]); *(LAS u32x2*)(sto + fr * 272 + (dt * 16 + fq * 4) * 2) = w2; }
.Lch_reb_done:
	s_or_b64 exec, exec, s[2:3]
	s_min_u32 s2, s37, 64
	s_add_i32 s38, s2, 3
	s_sub_i32 s2, 0x44, s2
	s_cmp_lg_u32 s35, 0
	s_cselect_b32 s39, s2, 0
	s_and_b64 s[2:3], s[78:79], exec
	s_cselect_b32 s38, s38, s39
	s_lshl_b32 s72, s38, 13
	s_lshl_b32 s39, s38, 14
	s_add_u32 s2, s1, s39
	s_addc_u32 s3, s30, 0
	v_lshl_add_u64 v[0:1], v[134:135], 1, s[2:3]
	v_lshl_add_u64 v[2:3], v[136:137], 1, s[2:3]
	s_add_u32 s2, s31, s39
	s_addc_u32 s3, s34, 0
	s_cmp_lt_u32 s38, 4
	v_lshl_add_u64 v[8:9], v[138:139], 1, s[2:3]
	v_lshl_add_u64 v[10:11], v[140:141], 1, s[2:3]
	s_waitcnt vmcnt(11)
	v_lshl_add_u64 v[20:21], v[150:151], 0, s[72:73]
	s_cselect_b64 vcc, -1, 0
	s_lshl_b32 s72, s38, 7
	s_movk_i32 s2, 0xfe00
	v_lshl_add_u64 v[18:19], v[146:147], 0, s[72:73]
	s_mov_b32 s3, -1
	v_mov_b32_e32 v143, v65
	v_lshl_add_u64 v[16:17], v[132:133], 0, s[72:73]
	v_lshl_add_u64 v[18:19], v[18:19], 0, s[2:3]
	s_lshl_b32 s72, s38, 9
	v_lshl_add_u64 v[0:1], v[0:1], 0, v[64:65]
	v_lshl_add_u64 v[4:5], v[2:3], 0, v[64:65]
	v_lshl_add_u64 v[8:9], v[8:9], 0, v[142:143]
	v_lshl_add_u64 v[12:13], v[10:11], 0, v[142:143]
	v_cndmask_b32_e32 v17, v19, v17, vcc
	v_cndmask_b32_e32 v16, v18, v16, vcc
	v_lshl_add_u64 v[22:23], v[152:153], 0, s[72:73]
	global_load_dwordx4 v[0:3], v[0:1], off
	s_nop 0
	global_load_dwordx4 v[4:7], v[4:5], off
	s_nop 0
	global_load_dwordx4 v[8:11], v[8:9], off
	s_nop 0
	global_load_dwordx4 v[12:15], v[12:13], off
	s_mov_b64 s[2:3], -1
	global_load_dwordx4 v[16:19], v[16:17], off
	s_nop 0
	global_load_dwordx4 v[24:27], v[20:21], off
	s_nop 0
	global_load_dwordx4 v[20:23], v[22:23], off
	ds_read_b128 v[126:129], v175 offset:45056
	ds_read_b128 v[122:125], v175 offset:45120
	s_and_b64 vcc, exec, s[26:27]
	s_mov_b64 s[2:3], -1
	s_cbranch_vccz .LBB0_460
	v_add_u32_e32 v143, v160, v161
	ds_read_b128 v[70:73], v143 offset:17408
	ds_read_b128 v[78:81], v160 offset:54272
	ds_read_b128 v[82:85], v143 offset:19712
	ds_read_b128 v[86:89], v160 offset:54336
	ds_read_b128 v[106:109], v143 offset:22016
	s_mov_b64 s[2:3], 0
	s_waitcnt lgkmcnt(3)
	v_pk_mul_f32 v[80:81], v[58:59], v[80:81]
	v_pk_mul_f32 v[78:79], v[56:57], v[78:79]
	s_waitcnt lgkmcnt(1)
	v_pk_mul_f32 v[88:89], v[62:63], v[88:89]
	v_pk_mul_f32 v[86:87], v[60:61], v[86:87]
	v_mfma_f32_16x16x32_bf16 v[70:73], v[70:73], v[126:129], v[78:81]
	s_nop 2
	ds_read_b128 v[78:81], v160 offset:54400
	v_mfma_f32_16x16x32_bf16 v[82:85], v[82:85], v[126:129], v[86:89]
	s_nop 2
	ds_read_b128 v[86:89], v143 offset:24320
	s_waitcnt lgkmcnt(1)
	v_pk_mul_f32 v[80:81], v[68:69], v[80:81]
	v_pk_mul_f32 v[78:79], v[66:67], v[78:79]
	s_nop 1
	v_mfma_f32_16x16x32_bf16 v[106:109], v[106:109], v[126:129], v[78:81]
	s_nop 2
	ds_read_b128 v[78:81], v160 offset:54464
	s_waitcnt lgkmcnt(0)
	v_pk_mul_f32 v[80:81], v[76:77], v[80:81]
	v_pk_mul_f32 v[78:79], v[74:75], v[78:79]
	s_nop 1
	v_mfma_f32_16x16x32_bf16 v[86:89], v[86:89], v[126:129], v[78:81]
	s_nop 2
	ds_read_b128 v[78:81], v143 offset:17472
	s_waitcnt lgkmcnt(0)
	v_mfma_f32_16x16x32_bf16 v[70:73], v[78:81], v[122:125], v[70:73]
	ds_read_b128 v[78:81], v143 offset:19776
	s_nop 6
	v_cvt_pk_bf16_f32 v208, v70, v71
	s_waitcnt lgkmcnt(0)
	v_mfma_f32_16x16x32_bf16 v[78:81], v[78:81], v[122:125], v[82:85]
	s_nop 2
	ds_read_b128 v[82:85], v143 offset:22080
	v_cvt_pk_bf16_f32 v209, v72, v73
	s_waitcnt lgkmcnt(0)
	v_mfma_f32_16x16x32_bf16 v[82:85], v[82:85], v[122:125], v[106:109]
	s_nop 2
	ds_read_b128 v[106:109], v143 offset:24384
	ds_read_b128 v[110:113], v143 offset:26624
	ds_read_b128 v[114:117], v160 offset:54528
	s_waitcnt lgkmcnt(0)
	v_pk_mul_f32 v[116:117], v[92:93], v[116:117]
	v_pk_mul_f32 v[114:115], v[90:91], v[114:115]
	v_mfma_f32_16x16x32_bf16 v[86:89], v[106:109], v[122:125], v[86:89]
	ds_read_b128 v[106:109], v160 offset:54592
	ds_read_b128 v[118:121], v143 offset:28928
	ds_read_b128 v[182:185], v160 offset:54656
	ds_read_b128 v[186:189], v143 offset:31232
	s_waitcnt lgkmcnt(3)
	v_pk_mul_f32 v[108:109], v[96:97], v[108:109]
	v_mfma_f32_16x16x32_bf16 v[110:113], v[110:113], v[126:129], v[114:117]
	v_mul_f32_e64 v106, v94, v106
	v_mul_f32_e64 v107, v95, v107
	s_waitcnt lgkmcnt(1)
	v_pk_mul_f32 v[184:185], v[104:105], v[184:185]
	v_pk_mul_f32 v[182:183], v[102:103], v[182:183]
	ds_read_b128 v[114:117], v143 offset:33536
	v_mfma_f32_16x16x32_bf16 v[118:121], v[118:121], v[126:129], v[106:109]
	s_nop 2
	ds_read_b128 v[106:109], v160 offset:54720
	s_waitcnt lgkmcnt(2)
	v_mfma_f32_16x16x32_bf16 v[182:185], v[186:189], v[126:129], v[182:185]
	ds_read_b128 v[186:189], v143 offset:26688
	s_waitcnt lgkmcnt(1)
	v_pk_mul_f32 v[108:109], v[100:101], v[108:109]
	v_pk_mul_f32 v[106:107], v[98:99], v[106:107]
	s_nop 1
	v_mfma_f32_16x16x32_bf16 v[190:193], v[114:117], v[126:129], v[106:109]
	ds_read_b128 v[114:117], v143 offset:28992
	s_waitcnt lgkmcnt(1)
	v_mfma_f32_16x16x32_bf16 v[106:109], v[186:189], v[122:125], v[110:113]
	ds_read_b128 v[186:189], v143 offset:31296
	ds_read_b128 v[204:207], v143 offset:33600
	s_waitcnt lgkmcnt(2)
	v_mfma_f32_16x16x32_bf16 v[110:113], v[114:117], v[122:125], v[118:121]
	s_nop 2
	v_add_u32_e32 v118, v170, v156
	v_add_u32_e32 v143, 0x4000, v118
	s_waitcnt lgkmcnt(1)
	v_mfma_f32_16x16x32_bf16 v[114:117], v[186:189], v[122:125], v[182:185]
	s_waitcnt lgkmcnt(0)
	v_mfma_f32_16x16x32_bf16 v[118:121], v[204:207], v[122:125], v[190:193]
	s_nop 0
	v_cvt_pk_bf16_f32 v182, v78, v79
	v_cvt_pk_bf16_f32 v183, v80, v81
	ds_write2_b64 v143, v[208:209], v[182:183] offset0:128 offset1:132
	v_cvt_pk_bf16_f32 v182, v82, v83
	v_cvt_pk_bf16_f32 v183, v84, v85
	v_cvt_pk_bf16_f32 v184, v86, v87
	v_cvt_pk_bf16_f32 v185, v88, v89
	ds_write2_b64 v143, v[182:183], v[184:185] offset0:136 offset1:140
	v_cvt_pk_bf16_f32 v182, v106, v107
	v_cvt_pk_bf16_f32 v183, v108, v109
	v_cvt_pk_bf16_f32 v184, v110, v111
	v_cvt_pk_bf16_f32 v185, v112, v113
	ds_write2_b64 v143, v[182:183], v[184:185] offset0:144 offset1:148
	v_cvt_pk_bf16_f32 v182, v114, v115
	v_cvt_pk_bf16_f32 v183, v116, v117
	v_cvt_pk_bf16_f32 v184, v118, v119
	v_cvt_pk_bf16_f32 v185, v120, v121
	ds_write2_b64 v143, v[182:183], v[184:185] offset0:152 offset1:156

; #define LAS __attribute__((address_space(3)))
; __device__ __forceinline__ unsigned pk2(float lo, float hi) { const v2f_t f = {lo, hi}; const v2bf_t b = __builtin_convertvector(f, v2bf_t); return __builtin_bit_cast(unsigned, b); }
; #define CH_ISSUE(ci, set) CH_ISSUE_X(ci, set)
; #define CH_WRITE(buf, set) CH_WRITE_X(buf, set)
; __device__ __forceinline__ void gla_chain(const Params& p, LAS unsigned char* lds) {
;     ...
;         } else {
;             LAS unsigned char* sto = st + ((ci + 1) & 1) * (4 * 4352);
; #pragma unroll
;             for (int hh = 0; hh < 2; ++hh) {
;                 f32x4 ev[4]; bf16x8 ak[4][2];
; #pragma unroll
;                 for (int d4 = 0; d4 < 4; ++d4) { const int dt = hh * 4 + d4; ev[d4] = *(const LAS f32x4*)(cur + CH_E + (dt * 16 + fq * 4) * 4);
; #pragma unroll
;                     for (int ks = 0; ks < 2; ++ks) ak[d4][ks] = *(const LAS bf16x8*)(cur + CH_KH + (dt * 16 + fr) * 144 + ks * 64 + fq * 16); }
; #pragma unroll
;                 for (int d4 = 0; d4 < 4; ++d4) S[hh * 4 + d4] = S[hh * 4 + d4] * ev[d4];
; #pragma unroll
;                 for (int ks = 0; ks < 2; ++ks)
; #pragma unroll
;                     for (int d4 = 0; d4 < 4; ++d4) S[hh * 4 + d4] = __builtin_amdgcn_mfma_f32_16x16x32_bf16(ak[d4][ks], a_v[ks], S[hh * 4 + d4], 0, 0, 0);
;             }
; #pragma unroll
;             for (int dt = 0; dt < 8; ++dt) { u32x2 w2; w2.x = pk2(S[dt][0], S[dt][1]); w2.y = pk2(S[dt][2], S[dt][3]); *(LAS u32x2*)(sto + fr * 272 + (dt * 16 + fq * 4) * 2) = w2; }
;     ...
;     for (int ci = 0; ci < 68; ci += 2) {
;         CH_ISSUE(ci + 2, SET_A);
;         step(ci, lds);
;         CH_WRITE(1, SET_B);
;         __syncthreads();
;         CH_ISSUE(ci + 3, SET_B);
;         step(ci + 1, lds + CH_BUF);
;         CH_WRITE(0, SET_A);
;         __syncthreads();
.Lch_mid:
	s_waitcnt lgkmcnt(0)
	s_barrier
	s_waitcnt vmcnt(13)
	ds_write_b128 v131, v[28:31]
	s_waitcnt vmcnt(12)
	ds_write_b128 v131, v[32:35] offset:8704
	s_waitcnt vmcnt(11)
	ds_write_b128 v155, v[36:39] offset:17408
	s_waitcnt vmcnt(10)
	ds_write_b128 v155, v[40:43] offset:26624
	s_waitcnt vmcnt(7)
	ds_write_b128 v155, v[52:55] offset:35840
	ds_write_b128 v155, v[48:51] offset:45056
	s_and_saveexec_b64 s[2:3], s[8:9]
	s_cbranch_execz .Lch_rea_done
	v_add_u32_e32 v28, 0, v173
	s_waitcnt vmcnt(7)
	ds_write_b128 v28, v[44:47] offset:54272
.Lch_rea_done:
	s_or_b64 exec, exec, s[2:3]
	s_add_i32 s36, s37, 2
	s_cmpk_gt_u32 s37, 0x41
	s_cselect_b64 s[28:29], -1, 0
	s_add_i32 s38, s37, 4
	s_min_u32 s38, s38, 0x43
	s_cmp_gt_u32 s38, 3
	s_cselect_b32 s2, 0x47, 3
	s_sub_i32 s39, s2, s38
	s_and_b64 s[2:3], s[78:79], exec
	s_cselect_b32 s2, s38, s39
	s_ashr_i32 s3, s2, 31
	s_lshl_b64 s[38:39], s[2:3], 13
	s_lshl_b64 s[40:41], s[2:3], 14
	s_add_u32 s42, s1, s40
	s_addc_u32 s43, s30, s41
	s_add_u32 s40, s31, s40
	s_addc_u32 s41, s34, s41
	s_cmp_lt_i32 s2, 4
	s_waitcnt vmcnt(11)
	v_lshl_add_u64 v[44:45], v[150:151], 0, s[38:39]
	s_cselect_b64 vcc, -1, 0
	s_lshl_b32 s38, s2, 6
	s_ashr_i32 s39, s38, 31
	v_lshl_add_u64 v[46:47], s[38:39], 1, v[132:133]
	s_mov_b32 s39, s73
	v_lshl_add_u64 v[48:49], s[38:39], 1, v[146:147]
	s_movk_i32 s38, 0xfe00
	s_mov_b32 s39, -1
	v_lshl_add_u64 v[28:29], v[134:135], 1, s[42:43]
	v_lshl_add_u64 v[30:31], v[136:137], 1, s[42:43]
	v_lshl_add_u64 v[36:37], v[138:139], 1, s[40:41]
	v_lshl_add_u64 v[38:39], v[140:141], 1, s[40:41]
	v_lshl_add_u64 v[48:49], v[48:49], 0, s[38:39]
	v_lshl_add_u64 v[28:29], v[28:29], 0, v[64:65]
	v_lshl_add_u64 v[32:33], v[30:31], 0, v[64:65]
	v_lshl_add_u64 v[36:37], v[36:37], 0, v[144:145]
	v_lshl_add_u64 v[40:41], v[38:39], 0, v[144:145]
	v_cndmask_b32_e32 v47, v49, v47, vcc
	v_cndmask_b32_e32 v46, v48, v46, vcc
	s_lshl_b64 s[2:3], s[2:3], 9
	global_load_dwordx4 v[28:31], v[28:29], off
	s_nop 0
	global_load_dwordx4 v[32:35], v[32:33], off
	s_nop 0
	global_load_dwordx4 v[36:39], v[36:37], off
	s_nop 0
	global_load_dwordx4 v[40:43], v[40:41], off
	global_load_dwordx4 v[48:51], v[46:47], off
	v_lshl_add_u64 v[46:47], v[152:153], 0, s[2:3]
	global_load_dwordx4 v[52:55], v[44:45], off
	s_nop 0
	global_load_dwordx4 v[44:47], v[46:47], off
	ds_read_b128 v[126:129], v180
	ds_read_b128 v[122:125], v180 offset:64
	s_and_b64 vcc, exec, s[26:27]
	s_mov_b64 s[2:3], -1
	s_cbranch_vccz .LBB0_466
	ds_read_b128 v[56:59], v181
	v_add_u32_e32 v143, 0x1aa00, v160
	ds_read_b128 v[60:63], v143
	ds_read_b128 v[66:69], v181 offset:2304
	ds_read_b128 v[74:77], v181 offset:4608
	ds_read_b128 v[90:93], v143 offset:64
	s_mov_b64 s[2:3], 0
	s_waitcnt lgkmcnt(3)
	v_pk_mul_f32 v[62:63], v[72:73], v[62:63]
	v_pk_mul_f32 v[60:61], v[70:71], v[60:61]
	s_waitcnt lgkmcnt(0)
	v_pk_mul_f32 v[92:93], v[80:81], v[92:93]
	v_pk_mul_f32 v[90:91], v[78:79], v[90:91]
	v_mfma_f32_16x16x32_bf16 v[56:59], v[56:59], v[126:129], v[60:63]
	s_nop 2
	ds_read_b128 v[60:63], v143 offset:128
	v_mfma_f32_16x16x32_bf16 v[66:69], v[66:69], v[126:129], v[90:93]
	s_nop 2
	ds_read_b128 v[90:93], v181 offset:6912
	s_waitcnt lgkmcnt(1)
	v_pk_mul_f32 v[62:63], v[84:85], v[62:63]
	v_pk_mul_f32 v[60:61], v[82:83], v[60:61]
	s_nop 1
	v_mfma_f32_16x16x32_bf16 v[74:77], v[74:77], v[126:129], v[60:63]
	s_nop 2
	ds_read_b128 v[60:63], v143 offset:192
	s_waitcnt lgkmcnt(0)
	v_pk_mul_f32 v[62:63], v[88:89], v[62:63]
	v_pk_mul_f32 v[60:61], v[86:87], v[60:61]
	s_nop 1
	v_mfma_f32_16x16x32_bf16 v[90:93], v[90:93], v[126:129], v[60:63]
	s_nop 2
	ds_read_b128 v[60:63], v181 offset:64
	s_waitcnt lgkmcnt(0)
	v_mfma_f32_16x16x32_bf16 v[56:59], v[60:63], v[122:125], v[56:59]
	ds_read_b128 v[60:63], v181 offset:2368
	s_waitcnt lgkmcnt(0)
	v_mfma_f32_16x16x32_bf16 v[60:63], v[60:63], v[122:125], v[66:69]
	s_nop 2
	ds_read_b128 v[66:69], v181 offset:4672
	s_waitcnt lgkmcnt(0)
	v_mfma_f32_16x16x32_bf16 v[66:69], v[66:69], v[122:125], v[74:77]
	s_nop 2
	ds_read_b128 v[74:77], v181 offset:6976
	ds_read_b128 v[94:97], v181 offset:9216
	ds_read_b128 v[98:101], v143 offset:256
	s_waitcnt lgkmcnt(0)
	v_pk_mul_f32 v[100:101], v[108:109], v[100:101]
	v_mfma_f32_16x16x32_bf16 v[74:77], v[74:77], v[122:125], v[90:93]
	s_nop 2
	ds_read_b128 v[90:93], v143 offset:320
	ds_read_b128 v[102:105], v181 offset:11520
	ds_read_b128 v[182:185], v143 offset:384
	ds_read_b128 v[186:189], v181 offset:13824
	v_pk_mul_f32 v[98:99], v[106:107], v[98:99]
	s_waitcnt lgkmcnt(3)
	v_pk_mul_f32 v[92:93], v[112:113], v[92:93]
	v_pk_mul_f32 v[90:91], v[110:111], v[90:91]
	s_waitcnt lgkmcnt(1)
	v_pk_mul_f32 v[184:185], v[116:117], v[184:185]
	v_pk_mul_f32 v[182:183], v[114:115], v[182:183]
	v_mfma_f32_16x16x32_bf16 v[94:97], v[94:97], v[126:129], v[98:101]
	ds_read_b128 v[190:193], v181 offset:11584
	s_nop 1
	ds_read_b128 v[98:101], v181 offset:16128
	v_mfma_f32_16x16x32_bf16 v[102:105], v[102:105], v[126:129], v[90:93]
	s_nop 2
	ds_read_b128 v[90:93], v143 offset:448
	s_waitcnt lgkmcnt(3)
	v_mfma_f32_16x16x32_bf16 v[182:185], v[186:189], v[126:129], v[182:185]
	ds_read_b128 v[186:189], v181 offset:9280
	v_add_u32_e32 v143, v170, v156
	s_waitcnt lgkmcnt(1)
	v_pk_mul_f32 v[92:93], v[120:121], v[92:93]
	v_pk_mul_f32 v[90:91], v[118:119], v[90:91]
	s_nop 1
	v_mfma_f32_16x16x32_bf16 v[98:101], v[98:101], v[126:129], v[90:93]
	s_waitcnt lgkmcnt(0)
	v_mfma_f32_16x16x32_bf16 v[90:93], v[186:189], v[122:125], v[94:97]
	ds_read_b128 v[186:189], v181 offset:13888
	ds_read_b128 v[204:207], v181 offset:16192
	v_mfma_f32_16x16x32_bf16 v[94:97], v[190:193], v[122:125], v[102:105]
	v_cvt_pk_bf16_f32 v190, v56, v57
	v_cvt_pk_bf16_f32 v191, v58, v59
	s_waitcnt lgkmcnt(1)
	v_mfma_f32_16x16x32_bf16 v[102:105], v[186:189], v[122:125], v[182:185]
	s_waitcnt lgkmcnt(0)
	v_mfma_f32_16x16x32_bf16 v[98:101], v[204:207], v[122:125], v[98:101]
	s_nop 0
	v_cvt_pk_bf16_f32 v182, v60, v61
	v_cvt_pk_bf16_f32 v183, v62, v63
	ds_write2_b64 v143, v[190:191], v[182:183] offset1:4
	v_cvt_pk_bf16_f32 v182, v66, v67
	v_cvt_pk_bf16_f32 v183, v68, v69
	v_cvt_pk_bf16_f32 v184, v74, v75
	v_cvt_pk_bf16_f32 v185, v76, v77
	ds_write2_b64 v143, v[182:183], v[184:185] offset0:8 offset1:12
	v_cvt_pk_bf16_f32 v182, v90, v91
	v_cvt_pk_bf16_f32 v183, v92, v93
	v_cvt_pk_bf16_f32 v184, v94, v95
	v_cvt_pk_bf16_f32 v185, v96, v97
	ds_write2_b64 v143, v[182:183], v[184:185] offset0:16 offset1:20
	v_cvt_pk_bf16_f32 v182, v102, v103
	v_cvt_pk_bf16_f32 v183, v104, v105
	v_cvt_pk_bf16_f32 v184, v98, v99
	v_cvt_pk_bf16_f32 v185, v100, v101
	ds_write2_b64 v143, v[182:183], v[184:185] offset0:24 offset1:28

; #define CH_ISSUE(ci, set) CH_ISSUE_X(ci, set)
; #define CH_WRITE(buf, set) CH_WRITE_X(buf, set)
; __device__ __forceinline__ void gla_chain(const Params& p, LAS unsigned char* lds) {
;     ...
;     for (int ci = 0; ci < 68; ci += 2) {
;         CH_ISSUE(ci + 2, SET_A);
;         step(ci, lds);
;         CH_WRITE(1, SET_B);
;         __syncthreads();
;         CH_ISSUE(ci + 3, SET_B);
;         step(ci + 1, lds + CH_BUF);
;         CH_WRITE(0, SET_A);
;         __syncthreads();
;     }
.LBB0_457:
	s_add_i32 s35, s35, -2
	s_andn2_b64 vcc, exec, s[28:29]
	s_mov_b32 s37, s36
	s_waitcnt lgkmcnt(0)
	s_barrier
	s_cbranch_vccnz .LBB0_458
	s_waitcnt vmcnt(0)

; __global__ void __launch_bounds__(512, 2) mega(Params p_unused) {
;     ...
;           if (l == 0) { const float* modp = (const float*)WSP(OFF_MODP) + 5 * 12288; float* MOD1 = (float*)WSP(OFF_MOD) + 5 * 12288;
;             for (int i = bid * 512 + threadIdx.x; i < 5 * 12288; i += G * 512) { float sacc = p.b_ada[12288 + i % 12288];
; #pragma unroll 8
;               for (int k = 0; k < 32; ++k) sacc += modp[(size_t)k * (2 * 5 * 12288) + i];
;               MOD1[i] = sacc; } } }
.LBB0_609:
	s_mov_b32 s17, 0
	s_waitcnt vmcnt(5)
	s_mov_b32 s16, 0x125bc000
	v_lshl_add_u64 v[8:9], v[0:1], 0, s[16:17]
	global_load_dword v204, v[8:9], off
	s_mov_b32 s16, 0x12634000
	v_lshl_add_u64 v[8:9], v[0:1], 0, s[16:17]
	global_load_dword v205, v[8:9], off
	s_mov_b32 s16, 0x126ac000
	v_lshl_add_u64 v[8:9], v[0:1], 0, s[16:17]
	global_load_dword v206, v[8:9], off
	s_mov_b32 s16, 0x12724000
	v_lshl_add_u64 v[8:9], v[0:1], 0, s[16:17]
	global_load_dword v207, v[8:9], off
	s_mov_b32 s16, 0x1279c000
	v_lshl_add_u64 v[8:9], v[0:1], 0, s[16:17]
	global_load_dword v208, v[8:9], off
	s_mov_b32 s16, 0x12814000
	v_lshl_add_u64 v[8:9], v[0:1], 0, s[16:17]
	global_load_dword v209, v[8:9], off
	s_mov_b32 s16, 0x1288c000
	v_lshl_add_u64 v[8:9], v[0:1], 0, s[16:17]
	global_load_dword v210, v[8:9], off
	s_mov_b32 s16, 0x12904000
	v_lshl_add_u64 v[8:9], v[0:1], 0, s[16:17]
	global_load_dword v211, v[8:9], off
	s_mov_b32 s16, 0x1297c000
	v_lshl_add_u64 v[8:9], v[0:1], 0, s[16:17]
	global_load_dword v212, v[8:9], off
	s_mov_b32 s16, 0x129f4000
	v_lshl_add_u64 v[8:9], v[0:1], 0, s[16:17]
	global_load_dword v213, v[8:9], off
	s_mov_b32 s16, 0x12a6c000
	v_lshl_add_u64 v[8:9], v[0:1], 0, s[16:17]
	global_load_dword v214, v[8:9], off
	s_mov_b32 s16, 0x12ae4000
	v_lshl_add_u64 v[8:9], v[0:1], 0, s[16:17]
	global_load_dword v215, v[8:9], off
	s_mov_b32 s16, 0x12b5c000
	v_lshl_add_u64 v[8:9], v[0:1], 0, s[16:17]
	global_load_dword v216, v[8:9], off
	s_mov_b32 s16, 0x12bd4000
	v_lshl_add_u64 v[8:9], v[0:1], 0, s[16:17]
	global_load_dword v217, v[8:9], off
	s_mov_b32 s16, 0x12c4c000
	v_lshl_add_u64 v[8:9], v[0:1], 0, s[16:17]
	global_load_dword v218, v[8:9], off
	s_mov_b32 s16, 0x12cc4000
	v_lshl_add_u64 v[8:9], v[0:1], 0, s[16:17]
	global_load_dword v219, v[8:9], off
	s_mov_b32 s16, 0x12d3c000
	v_lshl_add_u64 v[8:9], v[0:1], 0, s[16:17]
	global_load_dword v220, v[8:9], off
	s_mov_b32 s16, 0x12db4000
	v_lshl_add_u64 v[8:9], v[0:1], 0, s[16:17]
	global_load_dword v221, v[8:9], off
	s_mov_b32 s16, 0x12e2c000
	v_lshl_add_u64 v[8:9], v[0:1], 0, s[16:17]
	global_load_dword v222, v[8:9], off
	s_mov_b32 s16, 0x12ea4000
	v_lshl_add_u64 v[8:9], v[0:1], 0, s[16:17]
	global_load_dword v223, v[8:9], off
	s_mov_b32 s16, 0x12f1c000
	v_lshl_add_u64 v[8:9], v[0:1], 0, s[16:17]
	global_load_dword v224, v[8:9], off
	s_mov_b32 s16, 0x12f94000
	v_lshl_add_u64 v[8:9], v[0:1], 0, s[16:17]
	global_load_dword v225, v[8:9], off
	s_mov_b32 s16, 0x1300c000
	v_lshl_add_u64 v[8:9], v[0:1], 0, s[16:17]
	global_load_dword v226, v[8:9], off
	s_mov_b32 s16, 0x13084000
	v_lshl_add_u64 v[8:9], v[0:1], 0, s[16:17]
	global_load_dword v227, v[8:9], off
	s_mov_b32 s16, 0x130fc000
	v_lshl_add_u64 v[8:9], v[0:1], 0, s[16:17]
	global_load_dword v228, v[8:9], off
	s_mov_b32 s16, 0x13174000
	v_lshl_add_u64 v[8:9], v[0:1], 0, s[16:17]
	global_load_dword v229, v[8:9], off
	s_mov_b32 s16, 0x131ec000
	v_lshl_add_u64 v[8:9], v[0:1], 0, s[16:17]
	global_load_dword v230, v[8:9], off
	s_mov_b32 s16, 0x13264000
	v_lshl_add_u64 v[8:9], v[0:1], 0, s[16:17]
	global_load_dword v231, v[8:9], off
	s_mov_b32 s16, 0x132dc000
	v_lshl_add_u64 v[8:9], v[0:1], 0, s[16:17]
	global_load_dword v232, v[8:9], off
	s_mov_b32 s16, 0x13354000
	v_lshl_add_u64 v[8:9], v[0:1], 0, s[16:17]
	global_load_dword v233, v[8:9], off
	s_mov_b32 s16, 0x133cc000
	v_lshl_add_u64 v[8:9], v[0:1], 0, s[16:17]
	global_load_dword v234, v[8:9], off
	s_mov_b32 s16, 0x13444000
	v_lshl_add_u64 v[8:9], v[0:1], 0, s[16:17]
	global_load_dword v235, v[8:9], off
	s_waitcnt vmcnt(31)
	v_add_f32_e32 v3, v4, v204
	s_waitcnt vmcnt(30)
	v_add_f32_e32 v3, v3, v205
	s_waitcnt vmcnt(29)
	v_add_f32_e32 v3, v3, v206
	s_waitcnt vmcnt(28)
	v_add_f32_e32 v3, v3, v207
	s_waitcnt vmcnt(27)
	v_add_f32_e32 v3, v3, v208
	s_waitcnt vmcnt(26)
	v_add_f32_e32 v3, v3, v209
	s_waitcnt vmcnt(25)
	v_add_f32_e32 v3, v3, v210
	s_waitcnt vmcnt(24)
	v_add_f32_e32 v3, v3, v211
	s_waitcnt vmcnt(23)
	v_add_f32_e32 v3, v3, v212
	s_waitcnt vmcnt(22)
	v_add_f32_e32 v3, v3, v213
	s_waitcnt vmcnt(21)
	v_add_f32_e32 v3, v3, v214
	s_waitcnt vmcnt(20)
	v_add_f32_e32 v3, v3, v215
	s_waitcnt vmcnt(19)
	v_add_f32_e32 v3, v3, v216
	s_waitcnt vmcnt(18)
	v_add_f32_e32 v3, v3, v217
	s_waitcnt vmcnt(17)
	v_add_f32_e32 v3, v3, v218
	s_waitcnt vmcnt(16)
	v_add_f32_e32 v3, v3, v219
	s_waitcnt vmcnt(15)
	v_add_f32_e32 v3, v3, v220
	s_waitcnt vmcnt(14)
	v_add_f32_e32 v3, v3, v221
	s_waitcnt vmcnt(13)
	v_add_f32_e32 v3, v3, v222
	s_waitcnt vmcnt(12)
	v_add_f32_e32 v3, v3, v223
	s_waitcnt vmcnt(11)
	v_add_f32_e32 v3, v3, v224
	s_waitcnt vmcnt(10)
	v_add_f32_e32 v3, v3, v225
	s_waitcnt vmcnt(9)
	v_add_f32_e32 v3, v3, v226
	s_waitcnt vmcnt(8)
	v_add_f32_e32 v3, v3, v227
	s_waitcnt vmcnt(7)
	v_add_f32_e32 v3, v3, v228
	s_waitcnt vmcnt(6)
	v_add_f32_e32 v3, v3, v229
	s_waitcnt vmcnt(5)
	v_add_f32_e32 v3, v3, v230
	s_waitcnt vmcnt(4)
	v_add_f32_e32 v3, v3, v231
	s_waitcnt vmcnt(3)
	v_add_f32_e32 v3, v3, v232
	s_waitcnt vmcnt(2)
	v_add_f32_e32 v3, v3, v233
	s_waitcnt vmcnt(1)
	v_add_f32_e32 v3, v3, v234
	s_waitcnt vmcnt(0)
	v_add_f32_e32 v4, v3, v235
	v_readlane_b32 s16, v239, 62
	v_ashrrev_i32_e32 v3, 31, v2
	v_readlane_b32 s17, v239, 63
	v_lshl_add_u64 v[6:7], v[2:3], 2, s[14:15]
	v_add_u32_e32 v2, s16, v2
	s_mov_b32 s1, 0xefff
	v_readlane_b32 s16, v238, 0
	v_cmp_lt_i32_e32 vcc, s1, v2
	v_readlane_b32 s17, v238, 1
	s_or_b64 s[12:13], vcc, s[12:13]
	global_store_dword v[6:7], v4, off
	v_lshl_add_u64 v[0:1], v[0:1], 0, s[16:17]
	s_andn2_b64 exec, exec, s[12:13]
	s_cbranch_execnz .LBB0_608
